# v23 + merge-phase loads L1-bypassing (sc1) so the side workgroups' deferred SEAM3 acquire needs no L1 invalidate
# speedup vs baseline: 1.0008x; 1.0008x over previous
; __device__ __forceinline__ void store16_wt(void* p, u32x4 v) { asm volatile("global_store_dwordx4 %0, %1, off sc1\n\ts_nop 1" :: "v"(p), "v"(v) : "memory"); }
; #define MRG(F) o.F = pk_bf16((w0 * bflo(a.F) + w1 * bflo(bq.F) + w2 * bflo(cq.F)) * bflo(gq.F), (w0 * bfhi(a.F) + w1 * bfhi(bq.F) + w2 * bfhi(cq.F)) * bfhi(gq.F))
; __device__ __forceinline__ void merge_phase(u16* OG, const float* LSE, const u16* AG, int bid, int nb) {
;     for (int idx = bid * 512 + threadIdx.x; idx < TT * 64; idx += nb * 512) {
;         const int tok = idx >> 6, h = (idx >> 3) & 7, ch = idx & 7; const size_t off = (size_t)tok * 512 + h * 64 + 8 * ch;
;         const float l0 = LSE[(size_t)tok * 8 + h], l1 = LSE[(size_t)TT * 8 + (size_t)tok * 8 + h], l2 = LSE[(size_t)2 * TT * 8 + (size_t)tok * 8 + h];
;         const float m = fmaxf(l0, fmaxf(l1, l2)); float w0 = __builtin_amdgcn_exp2f(l0 - m), w1 = __builtin_amdgcn_exp2f(l1 - m), w2 = __builtin_amdgcn_exp2f(l2 - m);
;         const float inv = 1.0f / (w0 + w1 + w2); w0 *= inv; w1 *= inv; w2 *= inv;
;         const u32x4 a = *(const u32x4*)(OG + off), bq = *(const u32x4*)(OG + (size_t)TT * 512 + off), cq = *(const u32x4*)(OG + (size_t)2 * TT * 512 + off), gq = *(const u32x4*)(AG + off);
;         u32x4 o;
;     ...
;         MRG(x); MRG(y); MRG(z); MRG(w);
;     ...
;         store16_wt(OG + off, o);
.Ls3d_rel:
.Ls3d_skip:
	s_mov_b64 exec, s[6:7]
	s_barrier
	s_add_u32 s4, s76, 0x1000000
	s_addc_u32 s5, s77, 0
	s_lshl_b32 s6, s2, 9
	v_add_u32_e32 v1, s6, v188
	v_add_u32_e32 v0, 0xffff8000, v1
	s_mov_b32 s16, 0x100000
	v_cmp_gt_i32_e32 vcc, s16, v0
	s_and_saveexec_b64 s[6:7], vcc
	s_cbranch_execz .LBB0_450
	s_add_u32 s8, s78, 0x1b00000
	s_addc_u32 s9, s79, 0
	s_add_u32 s10, s76, 0x3000000
	s_addc_u32 s11, s77, 0
	s_add_u32 s12, s76, 0x2000000
	s_addc_u32 s13, s77, 0
	v_add_u32_e32 v2, 0xfffe0000, v1
	v_lshlrev_b32_e32 v3, 3, v0
	s_mov_b64 s[14:15], 0
	v_mov_b32_e32 v1, 0
	s_mov_b32 s17, 0x80000
	s_mov_b32 s18, 0xe7fff
.LBB0_449:
	v_add_u32_e32 v2, 0x18000, v2
	v_ashrrev_i32_e32 v4, 6, v2
	v_ashrrev_i32_e32 v5, 31, v4
	v_bfe_u32 v0, v2, 3, 3
	v_lshlrev_b64 v[6:7], 9, v[4:5]
	v_lshlrev_b64 v[4:5], 5, v[4:5]
	v_lshlrev_b32_e32 v9, 6, v0
	v_lshlrev_b32_e32 v0, 2, v0
	v_lshl_add_u64 v[4:5], s[8:9], 0, v[4:5]
	v_lshl_add_u64 v[20:21], v[4:5], 0, v[0:1]
	v_and_b32_e32 v8, 56, v3
	v_add_co_u32_e32 v22, vcc, s17, v20
	v_or3_b32 v6, v6, v9, v8
	s_nop 0
	v_addc_co_u32_e32 v23, vcc, 0, v21, vcc
	v_lshlrev_b64 v[4:5], 1, v[6:7]
	v_add_co_u32_e32 v24, vcc, s16, v20
	v_lshl_add_u64 v[26:27], s[76:77], 0, v[4:5]
	s_nop 0
	v_addc_co_u32_e32 v25, vcc, 0, v21, vcc
	v_lshl_add_u64 v[28:29], s[4:5], 0, v[4:5]
	v_lshl_add_u64 v[30:31], s[12:13], 0, v[4:5]
	v_lshl_add_u64 v[32:33], s[10:11], 0, v[4:5]
	global_load_dword v0, v[20:21], off sc1
	global_load_dword v40, v[22:23], off sc1
	global_load_dword v41, v[24:25], off sc1
	global_load_dwordx4 v[4:7], v[28:29], off sc1
	global_load_dwordx4 v[8:11], v[26:27], off sc1
	global_load_dwordx4 v[12:15], v[30:31], off sc1
	global_load_dwordx4 v[16:19], v[32:33], off sc1
	v_add_u32_e32 v3, 0xc0000, v3
	s_waitcnt vmcnt(4)
	v_max3_f32 v42, v0, v40, v41
	v_sub_f32_e32 v0, v0, v42
	s_waitcnt vmcnt(3)
	v_lshlrev_b32_e32 v20, 16, v4
	s_waitcnt vmcnt(2)
	v_and_b32_e32 v21, 0xffff0000, v8
	s_waitcnt vmcnt(0)
	v_lshlrev_b32_e32 v36, 16, v18
	v_and_b32_e32 v37, 0xffff0000, v18
	v_sub_f32_e32 v18, v40, v42
	v_lshlrev_b32_e32 v22, 16, v8
	v_and_b32_e32 v23, 0xffff0000, v4
	v_lshlrev_b32_e32 v24, 16, v12
	v_and_b32_e32 v25, 0xffff0000, v12
	v_lshlrev_b32_e32 v28, 16, v16
	v_and_b32_e32 v29, 0xffff0000, v16
	v_and_b32_e32 v31, 0xffff0000, v9
	v_lshlrev_b32_e32 v4, 16, v9
	v_lshlrev_b32_e32 v8, 16, v13
	v_and_b32_e32 v9, 0xffff0000, v13
	v_lshlrev_b32_e32 v12, 16, v17
	v_and_b32_e32 v13, 0xffff0000, v17
	v_lshlrev_b32_e32 v16, 16, v6
	v_and_b32_e32 v17, 0xffff0000, v10
	v_lshlrev_b32_e32 v32, 16, v10
	v_and_b32_e32 v33, 0xffff0000, v6
	v_lshlrev_b32_e32 v34, 16, v14
	v_and_b32_e32 v35, 0xffff0000, v14
	v_and_b32_e32 v39, 0xffff0000, v11
	v_lshlrev_b32_e32 v6, 16, v11
	v_lshlrev_b32_e32 v10, 16, v15
	v_and_b32_e32 v11, 0xffff0000, v15
	v_lshlrev_b32_e32 v14, 16, v19
	v_and_b32_e32 v15, 0xffff0000, v19
	v_sub_f32_e32 v40, v41, v42
	v_exp_f32_e32 v19, v0
	v_exp_f32_e32 v18, v18
	v_exp_f32_e32 v40, v40
	v_lshlrev_b32_e32 v30, 16, v5
	v_and_b32_e32 v5, 0xffff0000, v5
	v_add_f32_e32 v0, v19, v18
	v_add_f32_e32 v0, v40, v0
	v_div_scale_f32 v41, s[20:21], v0, v0, 1.0
	v_rcp_f32_e32 v43, v41
	v_div_scale_f32 v42, vcc, 1.0, v0, 1.0
	v_lshlrev_b32_e32 v38, 16, v7
	v_fma_f32 v44, -v41, v43, 1.0
	v_fmac_f32_e32 v43, v44, v43
	v_mul_f32_e32 v44, v42, v43
	v_fma_f32 v45, -v41, v44, v42
	v_fmac_f32_e32 v44, v45, v43
	v_fma_f32 v41, -v41, v44, v42
	v_div_fmas_f32 v41, v41, v43, v44
	v_div_fixup_f32 v0, v41, v0, 1.0
	v_and_b32_e32 v7, 0xffff0000, v7
	v_pk_mul_f32 v[18:19], v[18:19], v[0:1] op_sel_hi:[1,0]
	v_mul_f32_e32 v40, v40, v0
	v_pk_mul_f32 v[22:23], v[18:19], v[22:23] op_sel:[1,0] op_sel_hi:[0,1]
	v_pk_mul_f32 v[4:5], v[18:19], v[4:5] op_sel:[1,0] op_sel_hi:[0,1]
	v_pk_mul_f32 v[32:33], v[18:19], v[32:33] op_sel:[1,0] op_sel_hi:[0,1]
	v_pk_mul_f32 v[6:7], v[18:19], v[6:7] op_sel:[1,0] op_sel_hi:[0,1]
	v_pk_fma_f32 v[20:21], v[18:19], v[20:21], v[22:23]
	v_pk_fma_f32 v[4:5], v[18:19], v[30:31], v[4:5]
	v_pk_fma_f32 v[16:17], v[18:19], v[16:17], v[32:33]
	v_pk_fma_f32 v[6:7], v[18:19], v[38:39], v[6:7]
	v_pk_fma_f32 v[18:19], v[40:41], v[24:25], v[20:21] op_sel_hi:[0,1,1]
	v_pk_fma_f32 v[4:5], v[40:41], v[8:9], v[4:5] op_sel_hi:[0,1,1]
	v_pk_fma_f32 v[8:9], v[40:41], v[34:35], v[16:17] op_sel_hi:[0,1,1]
	v_pk_fma_f32 v[6:7], v[40:41], v[10:11], v[6:7] op_sel_hi:[0,1,1]
	v_pk_mul_f32 v[10:11], v[18:19], v[28:29]
	v_pk_mul_f32 v[12:13], v[4:5], v[12:13]
	v_pk_mul_f32 v[8:9], v[8:9], v[36:37]
	v_pk_mul_f32 v[14:15], v[6:7], v[14:15]
	v_cvt_pk_bf16_f32 v4, v10, v11
	v_cvt_pk_bf16_f32 v5, v12, v13
	v_cvt_pk_bf16_f32 v6, v8, v9
	v_cvt_pk_bf16_f32 v7, v14, v15
	global_store_dwordx4 v[26:27], v[4:7], off sc1
	s_nop 1
	v_cmp_lt_i32_e32 vcc, s18, v2
	s_or_b64 s[14:15], vcc, s[14:15]
	s_andn2_b64 exec, exec, s[14:15]
	s_cbranch_execnz .LBB0_449
